# diff attention loop: packed v_pk_fma_f32 beside the MFMAs split into scalar v_fmamk_f32 pairs (instruction selection, bit-identical)
# baseline (speedup 1.0000x reference)
; #define LAS __attribute__((address_space(3)))
; __device__ __forceinline__ float fast_exp2(float x) { return __builtin_amdgcn_exp2f(x); }
; template <int MODE, int NQ>
; __device__ __forceinline__ void attn_unit(LAS unsigned char* lds, const Params& P, int layer, int b, int h, int qb) {
;     ...
;             if (it + 2 < NT) { if (hf == 0) AT_GLOADK(AT_TILE(it + 2)); else AT_GLOADV(AT_TILE(it + 2)); }
;             f32x16 sc[NC];
; #pragma unroll
;             for (int cc = 0; cc < NC; ++cc) {
;                 sc[cc] = f32x16{};
; #pragma unroll
;                 for (int d0 = 0; d0 < ND0; ++d0) sc[cc] = __builtin_amdgcn_mfma_f32_32x32x16_bf16(kf[(cc % NMAP) * ND0 + d0], qf[cc][d0], sc[cc], 0, 0, 0);
;             }
;             __builtin_amdgcn_sched_barrier(0);
;             AT_VLOAD(cur, hf);
;             if (hf == 0) AT_KLOAD(cur, 1); else if (it + 1 < NT) AT_KLOAD(nxt, 0);
;             __builtin_amdgcn_sched_barrier(0);
;             bf16x8 pw[NC][2]; float rmrel[NC]; bool alive = false;
; #pragma unroll
;             for (int cc = 0; cc < NC; ++cc) {
;                 f32x16& s0 = sc[cc];
;                 float mn;
;                 if (MODE != 0) {
;                     const LAS f32x4* tp4 = (const LAS f32x4*)(tlane + (kt * 64 + hf * 32) * 4);
;                     float rm = -3e38f;
; #pragma unroll
;                     for (int g = 0; g < 4; ++g) { const f32x4 t4 = tp4[2 * g];
; #pragma unroll
;                         for (int i = 0; i < 4; ++i) { s0[4 * g + i] = s0[4 * g + i] * c + t4[i]; rm = fmaxf(rm, s0[4 * g + i]); } }
;                     rm = xmax(rm);
;                     mn = fmaxf(mrun[cc], rm);
;                     rmrel[cc] = rm;
;                 } else {
;                     float rm = -3e38f;
; #pragma unroll
;                     for (int r = 0; r < 16; ++r) rm = fmaxf(rm, s0[r]);
;                     rm = xmax(rm);
;                     mn = fmaxf(mrun[cc], rm * c);
;                 }
;                 if (__any(mn > mrun[cc] + AT_THR)) {
;                     const float al = fast_exp2(mrun[cc] - mn); lrun[cc] *= al;
; #pragma unroll
;                     for (int r = 0; r < 16; ++r) { o[cc][0][r] *= al; o[cc][1][r] *= al; }
;                     mrun[cc] = mn;
;                 }
.LBB0_410:
	s_mul_i32 s10, s9, 0x5000
	s_add_i32 s16, s10, 0
	s_add_i32 s10, s5, s8
	s_add_i32 s11, s10, 0xffffe000
	s_cmp_gt_u32 s7, 31
	v_add3_u32 v0, s16, v193, v192
	s_cselect_b32 s10, s11, s10
	v_add_u32_e32 v199, v0, v189
	v_add_u32_e32 v0, s10, v191
	s_add_i32 s10, s7, 2
	s_sub_i32 s11, s7, 30
	s_cmp_gt_u32 s10, 31
	s_cselect_b32 s10, s11, s10
	s_ashr_i32 s11, s10, 31
	s_lshl_b64 s[10:11], s[10:11], 6
	v_lshl_add_u64 v[2:3], v[182:183], 0, s[10:11]
	v_mov_b64_e32 v[4:5], s[0:1]
	v_mad_u64_u32 v[4:5], s[14:15], v2, s27, v[4:5]
	v_mad_i32_i24 v5, v3, s27, v5
	global_load_dwordx4 v[2:5], v[4:5], off
	v_lshl_add_u64 v[228:229], v[178:179], 0, s[10:11]
	v_mad_u64_u32 v[230:231], s[14:15], v228, s27, v[180:181]
	v_mad_i32_i24 v231, v229, s27, v231
	global_load_dwordx4 v[224:227], v[230:231], off
	s_waitcnt lgkmcnt(3)
	v_mfma_f32_32x32x16_bf16 v[96:111], v[140:143], v[124:127], 0
	s_waitcnt lgkmcnt(1)
	v_mfma_f32_32x32x16_bf16 v[80:95], v[132:135], v[120:123], 0
	v_mfma_f32_32x32x16_bf16 v[96:111], v[136:139], v[116:119], v[96:111]
	s_waitcnt lgkmcnt(0)
	v_mfma_f32_32x32x16_bf16 v[80:95], v[128:131], v[112:115], v[80:95]
	ds_read_b64_tr_b16 v[148:149], v199 offset:12288
	ds_read_b64_tr_b16 v[150:151], v199 offset:12800
	ds_read_b64_tr_b16 v[144:145], v199 offset:13312
	ds_read_b64_tr_b16 v[146:147], v199 offset:13824
	ds_read_b64_tr_b16 v[140:141], v199 offset:16384
	ds_read_b64_tr_b16 v[142:143], v199 offset:16896
	ds_read_b64_tr_b16 v[136:137], v199 offset:17408
	ds_read_b64_tr_b16 v[138:139], v199 offset:17920
	v_add3_u32 v6, s16, v195, v196
	ds_read_b128 v[132:135], v6 offset:512
	ds_read_b128 v[128:131], v6 offset:2560
	ds_read_b128 v[10:13], v6 offset:4608
	ds_read_b128 v[6:9], v6 offset:6656
	ds_read_b128 v[156:159], v0 offset:61440
	ds_read_b128 v[152:155], v0 offset:61472
	ds_read_b128 v[164:167], v0 offset:61504
	ds_read_b128 v[172:175], v0 offset:61536
	s_waitcnt lgkmcnt(3)
	v_fmamk_f32 v160, v96, 0x3e8293ee, v156
	v_fmamk_f32 v161, v97, 0x3e8293ee, v157
	v_fmamk_f32 v98, v98, 0x3e8293ee, v158
	v_fmamk_f32 v99, v99, 0x3e8293ee, v159
	v_max3_f32 v96, v160, s68, v161
	s_waitcnt lgkmcnt(2)
	v_fmamk_f32 v14, v100, 0x3e8293ee, v152
	v_fmamk_f32 v15, v101, 0x3e8293ee, v153
	v_max3_f32 v96, v96, v98, v99
	v_max3_f32 v100, v96, v14, v15
	v_fmamk_f32 v96, v102, 0x3e8293ee, v154
	v_fmamk_f32 v97, v103, 0x3e8293ee, v155
	s_waitcnt lgkmcnt(1)
	v_fmamk_f32 v104, v104, 0x3e8293ee, v164
	v_fmamk_f32 v105, v105, 0x3e8293ee, v165
	v_max3_f32 v100, v100, v96, v97
	v_max3_f32 v102, v100, v104, v105
	v_fmamk_f32 v100, v106, 0x3e8293ee, v166
	v_fmamk_f32 v101, v107, 0x3e8293ee, v167
	s_nop 0
	v_max3_f32 v106, v102, v100, v101
	s_waitcnt lgkmcnt(0)
	v_fmamk_f32 v102, v108, 0x3e8293ee, v172
	v_fmamk_f32 v103, v109, 0x3e8293ee, v173
	s_nop 0
	v_max3_f32 v108, v106, v102, v103
	v_fmamk_f32 v106, v110, 0x3e8293ee, v174
	v_fmamk_f32 v107, v111, 0x3e8293ee, v175
	s_nop 0
	v_max3_f32 v108, v108, v106, v107
	v_mov_b32_e32 v109, v108
	s_nop 1
	v_permlane32_swap_b32_e32 v108, v109
	v_max_f32_e32 v108, v108, v109
	v_max_f32_e32 v200, v198, v108
	v_add_f32_e32 v109, 0x41000000, v198
	v_cmp_gt_f32_e32 vcc, v200, v109
	s_cbranch_vccz .LBB0_412
	v_sub_f32_e32 v109, v198, v200
	s_mov_b32 s61, 0
	v_exp_f32_e32 v110, v109
	s_nop 0
	v_mul_f32_e32 v188, v188, v110
	v_pk_mul_f32 v[78:79], v[78:79], v[110:111] op_sel_hi:[1,0]
	v_pk_mul_f32 v[76:77], v[76:77], v[110:111] op_sel_hi:[1,0]
	v_pk_mul_f32 v[74:75], v[74:75], v[110:111] op_sel_hi:[1,0]
	v_pk_mul_f32 v[72:73], v[72:73], v[110:111] op_sel_hi:[1,0]
	v_pk_mul_f32 v[70:71], v[70:71], v[110:111] op_sel_hi:[1,0]
	v_pk_mul_f32 v[68:69], v[68:69], v[110:111] op_sel_hi:[1,0]
	v_pk_mul_f32 v[66:67], v[66:67], v[110:111] op_sel_hi:[1,0]
	v_pk_mul_f32 v[64:65], v[64:65], v[110:111] op_sel_hi:[1,0]
	v_pk_mul_f32 v[30:31], v[30:31], v[110:111] op_sel_hi:[1,0]
	v_pk_mul_f32 v[28:29], v[28:29], v[110:111] op_sel_hi:[1,0]
	v_pk_mul_f32 v[26:27], v[26:27], v[110:111] op_sel_hi:[1,0]
	v_pk_mul_f32 v[24:25], v[24:25], v[110:111] op_sel_hi:[1,0]
	v_pk_mul_f32 v[22:23], v[22:23], v[110:111] op_sel_hi:[1,0]
	v_pk_mul_f32 v[20:21], v[20:21], v[110:111] op_sel_hi:[1,0]
	v_pk_mul_f32 v[18:19], v[18:19], v[110:111] op_sel_hi:[1,0]
	v_pk_mul_f32 v[16:17], v[16:17], v[110:111] op_sel_hi:[1,0]
	s_branch .LBB0_413

; template <int MODE, int NQ>
; __device__ __forceinline__ void attn_unit(LAS unsigned char* lds, const Params& P, int layer, int b, int h, int qb) {
;     ...
;         const int bnx = (bcur == 2) ? 0 : bcur + 1, bn2 = (bnx == 2) ? 0 : bnx + 1;
;         const LAS unsigned char* cur = lds + bcur * AT_BUF;
;         const LAS unsigned char* nxt = lds + bnx * AT_BUF;
; #pragma unroll
;         for (int hf = 0; hf < 2; ++hf) {
;             if (it + 2 < NT) { if (hf == 0) AT_GLOADK(AT_TILE(it + 2)); else AT_GLOADV(AT_TILE(it + 2)); }
;             f32x16 sc[NC];
; #pragma unroll
;             for (int cc = 0; cc < NC; ++cc) {
;                 sc[cc] = f32x16{};
; #pragma unroll
;                 for (int d0 = 0; d0 < ND0; ++d0) sc[cc] = __builtin_amdgcn_mfma_f32_32x32x16_bf16(kf[(cc % NMAP) * ND0 + d0], qf[cc][d0], sc[cc], 0, 0, 0);
;             }
;             __builtin_amdgcn_sched_barrier(0);
;             AT_VLOAD(cur, hf);
;             if (hf == 0) AT_KLOAD(cur, 1); else if (it + 1 < NT) AT_KLOAD(nxt, 0);
;             __builtin_amdgcn_sched_barrier(0);
;             bf16x8 pw[NC][2]; float rmrel[NC]; bool alive = false;
; #pragma unroll
;             for (int cc = 0; cc < NC; ++cc) {
;                 f32x16& s0 = sc[cc];
;                 float mn;
;                 if (MODE != 0) {
;                     const LAS f32x4* tp4 = (const LAS f32x4*)(tlane + (kt * 64 + hf * 32) * 4);
;                     float rm = -3e38f;
; #pragma unroll
;                     for (int g = 0; g < 4; ++g) { const f32x4 t4 = tp4[2 * g];
; #pragma unroll
;                         for (int i = 0; i < 4; ++i) { s0[4 * g + i] = s0[4 * g + i] * c + t4[i]; rm = fmaxf(rm, s0[4 * g + i]); } }
;                     rm = xmax(rm);
;                     mn = fmaxf(mrun[cc], rm);
;                     rmrel[cc] = rm;
;                 } else {
;                     float rm = -3e38f;
; #pragma unroll
;                     for (int r = 0; r < 16; ++r) rm = fmaxf(rm, s0[r]);
;                     rm = xmax(rm);
;                     mn = fmaxf(mrun[cc], rm * c);
;                 }
;                 if (__any(mn > mrun[cc] + AT_THR)) {
;                     const float al = fast_exp2(mrun[cc] - mn); lrun[cc] *= al;
; #pragma unroll
;                     for (int r = 0; r < 16; ++r) { o[cc][0][r] *= al; o[cc][1][r] *= al; }
;                     mrun[cc] = mn;
;                 }
.LBB0_422:
	s_add_i32 s14, s9, 1
	s_cmp_lg_u32 s9, 2
	s_cselect_b32 s9, s14, 0
	s_mul_i32 s15, s9, 0x5000
	s_add_i32 s10, s15, 0x5000
	s_cmp_lg_u32 s9, 2
	s_cselect_b32 s14, s10, 0
	v_add_u32_e32 v202, s14, v194
	v_mfma_f32_32x32x16_bf16 v[96:111], v[132:135], v[124:127], 0
	v_mfma_f32_32x32x16_bf16 v[80:95], v[10:13], v[120:123], 0
	v_mfma_f32_32x32x16_bf16 v[96:111], v[128:131], v[116:119], v[96:111]
	v_mfma_f32_32x32x16_bf16 v[80:95], v[6:9], v[112:115], v[80:95]
	ds_read_b64_tr_b16 v[148:149], v199 offset:14336
	ds_read_b64_tr_b16 v[150:151], v199 offset:14848
	ds_read_b64_tr_b16 v[144:145], v199 offset:15360
	ds_read_b64_tr_b16 v[146:147], v199 offset:15872
	ds_read_b64_tr_b16 v[10:11], v199 offset:18432
	ds_read_b64_tr_b16 v[12:13], v199 offset:18944
	ds_read_b64_tr_b16 v[6:7], v199 offset:19456
	ds_read_b64_tr_b16 v[8:9], v199 offset:19968
	v_add_u32_e32 v14, s15, v190
	ds_read_b128 v[140:143], v14
	ds_read_b128 v[136:139], v14 offset:2048
	ds_read_b128 v[132:135], v14 offset:4096
	ds_read_b128 v[128:131], v14 offset:6144
	ds_read_b128 v[156:159], v0 offset:61568
	ds_read_b128 v[152:155], v0 offset:61600
	ds_read_b128 v[164:167], v0 offset:61632
	ds_read_b128 v[172:175], v0 offset:61664
	s_waitcnt lgkmcnt(3)
	v_fmamk_f32 v160, v96, 0x3e8293ee, v156
	v_fmamk_f32 v161, v97, 0x3e8293ee, v157
	v_fmamk_f32 v98, v98, 0x3e8293ee, v158
	v_fmamk_f32 v99, v99, 0x3e8293ee, v159
	v_max3_f32 v96, v160, s68, v161
	s_waitcnt lgkmcnt(2)
	v_fmamk_f32 v14, v100, 0x3e8293ee, v152
	v_fmamk_f32 v15, v101, 0x3e8293ee, v153
	v_max3_f32 v96, v96, v98, v99
	v_max3_f32 v100, v96, v14, v15
	v_fmamk_f32 v96, v102, 0x3e8293ee, v154
	v_fmamk_f32 v97, v103, 0x3e8293ee, v155
	s_waitcnt lgkmcnt(1)
	v_fmamk_f32 v104, v104, 0x3e8293ee, v164
	v_fmamk_f32 v105, v105, 0x3e8293ee, v165
	v_max3_f32 v100, v100, v96, v97
	v_max3_f32 v0, v100, v104, v105
	v_fmamk_f32 v100, v106, 0x3e8293ee, v166
	v_fmamk_f32 v101, v107, 0x3e8293ee, v167
	s_waitcnt lgkmcnt(0)
	v_fmamk_f32 v102, v108, 0x3e8293ee, v172
	v_fmamk_f32 v103, v109, 0x3e8293ee, v173
	v_max3_f32 v0, v0, v100, v101
	v_max3_f32 v0, v0, v102, v103
	v_fmamk_f32 v106, v110, 0x3e8293ee, v174
	v_fmamk_f32 v107, v111, 0x3e8293ee, v175
	s_nop 0
	v_max3_f32 v0, v0, v106, v107
	v_mov_b32_e32 v108, v0
	s_nop 1
	v_permlane32_swap_b32_e32 v0, v108
	v_max_f32_e32 v0, v0, v108
	v_max_f32_e32 v198, v200, v0
	v_add_f32_e32 v108, 0x41000000, v200
	v_cmp_gt_f32_e32 vcc, v198, v108
	s_cbranch_vccz .LBB0_424
	v_sub_f32_e32 v108, v200, v198
	s_mov_b32 s61, 0
	v_exp_f32_e32 v108, v108
	s_nop 0
	v_mul_f32_e32 v188, v188, v108
	v_pk_mul_f32 v[78:79], v[78:79], v[108:109] op_sel_hi:[1,0]
	v_pk_mul_f32 v[76:77], v[76:77], v[108:109] op_sel_hi:[1,0]
	v_pk_mul_f32 v[74:75], v[74:75], v[108:109] op_sel_hi:[1,0]
	v_pk_mul_f32 v[72:73], v[72:73], v[108:109] op_sel_hi:[1,0]
	v_pk_mul_f32 v[70:71], v[70:71], v[108:109] op_sel_hi:[1,0]
	v_pk_mul_f32 v[68:69], v[68:69], v[108:109] op_sel_hi:[1,0]
	v_pk_mul_f32 v[66:67], v[66:67], v[108:109] op_sel_hi:[1,0]
	v_pk_mul_f32 v[64:65], v[64:65], v[108:109] op_sel_hi:[1,0]
	v_pk_mul_f32 v[30:31], v[30:31], v[108:109] op_sel_hi:[1,0]
	v_pk_mul_f32 v[28:29], v[28:29], v[108:109] op_sel_hi:[1,0]
	v_pk_mul_f32 v[26:27], v[26:27], v[108:109] op_sel_hi:[1,0]
	v_pk_mul_f32 v[24:25], v[24:25], v[108:109] op_sel_hi:[1,0]
	v_pk_mul_f32 v[22:23], v[22:23], v[108:109] op_sel_hi:[1,0]
	v_pk_mul_f32 v[20:21], v[20:21], v[108:109] op_sel_hi:[1,0]
	v_pk_mul_f32 v[18:19], v[18:19], v[108:109] op_sel_hi:[1,0]
	v_pk_mul_f32 v[16:17], v[16:17], v[108:109] op_sel_hi:[1,0]
	s_branch .LBB0_425
